# ml_out six tile loads issued together (both direction copies) + gates_gemm fragment loads batched with counted waits, on top of lru_pass DMA prefetch/caches
# speedup vs baseline: 1.0333x; 1.0049x over previous
; #define LAS __attribute__((address_space(3)))
; __device__ __forceinline__ bf16_t f2bf(float f) { return (bf16_t)(cvt_pk_bf16(f, 0.f) & 0xffffu); }
; __device__ __forceinline__ float bf2f(bf16_t b) { return __uint_as_float(((unsigned)b) << 16); }
; __device__ __forceinline__ void ml_out(LAS unsigned char* L, const bf16_t* Z, const float* GATES, const bf16_t* MLC, const float* MLDN, const float* MLM, const float* gain, bf16_t* Y) {
;     ...
;             { const int i = tid >> 3, sg = tid & 7; const int t = g ? (64 * c + 63 - i) : (64 * c + i); const bf16_t* zr = Z + ((size_t)b * S_ + t) * 2560;
;                 *(LAS bf16x8*)(Qs + i * 72 + sg * 8) = *(const bf16x8*)(zr + h * 64 + sg * 8);
;                 *(LAS bf16x8*)(Ks + i * 72 + sg * 8) = *(const bf16x8*)(zr + 256 + h * 64 + sg * 8);
; #pragma unroll
;                 for (int hh = 0; hh < 2; ++hh) { const bf16x8 vv = *(const bf16x8*)(zr + 512 + h * 128 + (sg + 8 * hh) * 8);
; #pragma unroll
;                     for (int e = 0; e < 8; ++e) Vt[((sg + 8 * hh) * 8 + e) * 72 + i] = (bf16_t)vv[e]; }
; #pragma unroll
;                 for (int hh = 0; hh < 2; ++hh) { const int idx = tid + 512 * hh, v = idx >> 3, s8 = idx & 7;
;                     *(LAS bf16x8*)(Cs + v * 72 + s8 * 8) = *(const bf16x8*)(MLC + (size_t)it * 8192 + v * 64 + s8 * 8); } }
;             __syncthreads();
;             { const int i = tid >> 3, p = tid & 7; const float wi = wint[i]; float part = 0.f;
; #pragma unroll
;                 for (int e = 0; e < 8; ++e) { const float q = bf2f(Qs[i * 72 + p * 8 + e]); Qw[i * 72 + p * 8 + e] = f2bf(q * wi); part += nv[p * 8 + e] * q; }
;                 part += __shfl_xor(part, 1); part += __shfl_xor(part, 2); part += __shfl_xor(part, 4);
;                 if (p == 0) deni[i] = part * wi; }
.LBB0_530:
	s_or_b64 exec, exec, s[38:39]
	v_add_u32_e32 v4, s84, v26
	v_readlane_b32 s2, v251, 26
	s_lshl_b64 s[20:21], s[20:21], 14
	v_ashrrev_i32_e32 v5, 31, v4
	v_readlane_b32 s3, v251, 27
	v_lshl_add_u64 v[4:5], s[20:21], 0, v[4:5]
	s_lshl_b32 s28, s85, 7
	v_mov_b64_e32 v[6:7], s[2:3]
	s_movk_i32 s2, 0x1400
	v_mad_u64_u32 v[8:9], s[4:5], v4, s2, v[6:7]
	v_mad_i32_i24 v9, v5, s2, v9
	v_lshl_add_u64 v[4:5], v[8:9], 0, s[28:29]
	v_mov_b32_e32 v41, v0
	v_lshl_add_u64 v[10:11], v[4:5], 0, v[40:41]
	global_load_dwordx4 v[112:115], v[10:11], off
	global_load_dwordx4 v[116:119], v[10:11], off offset:512
	s_mov_b32 s25, s29
	v_lshlrev_b64 v[2:3], 14, v[2:3]
	v_add_u32_e32 v22, v48, v46
	v_lshl_add_u64 v[4:5], v[8:9], 0, s[24:25]
	v_lshl_add_u64 v[8:9], v[4:5], 0, v[40:41]
	global_load_dwordx4 v[120:123], v[8:9], off offset:1024
	global_load_dwordx4 v[124:127], v[8:9], off offset:1152
	v_lshl_add_u64 v[6:7], v[28:29], 0, v[2:3]
	v_lshl_add_u64 v[2:3], v[34:35], 1, v[6:7]
	global_load_dwordx4 v[128:131], v[2:3], off
	v_lshl_add_u64 v[2:3], v[36:37], 1, v[6:7]
	global_load_dwordx4 v[132:135], v[2:3], off
	s_waitcnt vmcnt(5)
	ds_write_b128 v47, v[112:115]
	s_waitcnt vmcnt(4)
	ds_write_b128 v47, v[116:119] offset:9216
	s_waitcnt vmcnt(3)
	ds_write_b16 v97, v120 offset:18432
	ds_write_b16_d16_hi v97, v120 offset:18576
	ds_write_b16 v97, v121 offset:18720
	ds_write_b16_d16_hi v97, v121 offset:18864
	ds_write_b16 v97, v122 offset:19008
	ds_write_b16_d16_hi v97, v122 offset:19152
	ds_write_b16 v97, v123 offset:19296
	ds_write_b16_d16_hi v97, v123 offset:19440
	s_waitcnt vmcnt(2)
	ds_write_b16 v98, v124 offset:18432
	ds_write_b16_d16_hi v97, v124 offset:27792
	ds_write_b16 v97, v125 offset:27936
	ds_write_b16_d16_hi v97, v125 offset:28080
	ds_write_b16 v97, v126 offset:28224
	ds_write_b16_d16_hi v97, v126 offset:28368
	ds_write_b16 v97, v127 offset:28512
	ds_write_b16_d16_hi v97, v127 offset:28656
	s_waitcnt vmcnt(1)
	ds_write_b128 v22, v[128:131] offset:36864
	s_waitcnt vmcnt(0)
	ds_write_b128 v99, v[132:135] offset:36864
	s_waitcnt lgkmcnt(0)
	s_barrier
	ds_read_b32 v2, v49
	ds_read_b128 v[4:7], v50
	ds_read_b128 v[8:11], v50 offset:16
	ds_read_b128 v[12:15], v47
	s_waitcnt lgkmcnt(0)
	v_lshlrev_b32_e32 v20, 16, v12
	v_and_b32_e32 v21, 0xffff0000, v12
	v_fma_f32 v3, v4, v20, 0
	v_lshlrev_b32_e32 v16, 16, v13
	v_fmac_f32_e32 v3, v5, v21
	v_and_b32_e32 v17, 0xffff0000, v13
	v_fmac_f32_e32 v3, v6, v16
	v_pk_mul_f32 v[4:5], v[2:3], v[16:17] op_sel_hi:[0,1]
	v_pk_mul_f32 v[12:13], v[2:3], v[20:21] op_sel_hi:[0,1]
	v_fmac_f32_e32 v3, v7, v17
	v_lshlrev_b32_e32 v6, 16, v14
	v_and_b32_e32 v7, 0xffff0000, v14
	v_fmac_f32_e32 v3, v8, v6
	v_lshlrev_b32_e32 v16, 16, v15
	v_fmac_f32_e32 v3, v9, v7
	v_and_b32_e32 v17, 0xffff0000, v15
	v_fmac_f32_e32 v3, v10, v16
	v_pk_mul_f32 v[8:9], v[2:3], v[16:17] op_sel_hi:[0,1]
	v_pk_mul_f32 v[14:15], v[2:3], v[6:7] op_sel_hi:[0,1]
	v_cvt_pk_bf16_f32 v7, v8, v9
	v_cvt_pk_bf16_f32 v6, v14, v15
	v_cvt_pk_bf16_f32 v5, v4, v5
	v_cvt_pk_bf16_f32 v4, v12, v13
	v_fmac_f32_e32 v3, v11, v17
	ds_write_b128 v47, v[4:7] offset:64512
	ds_bpermute_b32 v4, v51, v3
	s_waitcnt lgkmcnt(0)
	v_add_f32_e32 v3, v3, v4
	ds_bpermute_b32 v4, v52, v3
	s_waitcnt lgkmcnt(0)
	v_add_f32_e32 v3, v3, v4
	ds_bpermute_b32 v4, v53, v3
	s_and_saveexec_b64 s[24:25], s[42:43]
	s_cbranch_execz .LBB0_532
	s_waitcnt lgkmcnt(0)
	v_add_f32_e32 v3, v3, v4
	v_mul_f32_e32 v2, v2, v3
	ds_write_b32 v60, v2

; #define LAS __attribute__((address_space(3)))
; __device__ __forceinline__ bf16_t f2bf(float f) { return (bf16_t)(cvt_pk_bf16(f, 0.f) & 0xffffu); }
; __device__ __forceinline__ float bf2f(bf16_t b) { return __uint_as_float(((unsigned)b) << 16); }
; __device__ __forceinline__ void ml_out(LAS unsigned char* L, const bf16_t* Z, const float* GATES, const bf16_t* MLC, const float* MLDN, const float* MLM, const float* gain, bf16_t* Y) {
;     ...
;             { const int i = tid >> 3, sg = tid & 7; const int t = g ? (64 * c + 63 - i) : (64 * c + i); const bf16_t* zr = Z + ((size_t)b * S_ + t) * 2560;
;                 *(LAS bf16x8*)(Qs + i * 72 + sg * 8) = *(const bf16x8*)(zr + h * 64 + sg * 8);
;                 *(LAS bf16x8*)(Ks + i * 72 + sg * 8) = *(const bf16x8*)(zr + 256 + h * 64 + sg * 8);
; #pragma unroll
;                 for (int hh = 0; hh < 2; ++hh) { const bf16x8 vv = *(const bf16x8*)(zr + 512 + h * 128 + (sg + 8 * hh) * 8);
; #pragma unroll
;                     for (int e = 0; e < 8; ++e) Vt[((sg + 8 * hh) * 8 + e) * 72 + i] = (bf16_t)vv[e]; }
; #pragma unroll
;                 for (int hh = 0; hh < 2; ++hh) { const int idx = tid + 512 * hh, v = idx >> 3, s8 = idx & 7;
;                     *(LAS bf16x8*)(Cs + v * 72 + s8 * 8) = *(const bf16x8*)(MLC + (size_t)it * 8192 + v * 64 + s8 * 8); } }
;             __syncthreads();
;             { const int i = tid >> 3, p = tid & 7; const float wi = wint[i]; float part = 0.f;
; #pragma unroll
;                 for (int e = 0; e < 8; ++e) { const float q = bf2f(Qs[i * 72 + p * 8 + e]); Qw[i * 72 + p * 8 + e] = f2bf(q * wi); part += nv[p * 8 + e] * q; }
;                 part += __shfl_xor(part, 1); part += __shfl_xor(part, 2); part += __shfl_xor(part, 4);
;                 if (p == 0) deni[i] = part * wi; }
.LBB0_560:
	s_or_b64 exec, exec, s[26:27]
	v_sub_u32_e32 v4, s84, v26
	v_add_u32_e32 v4, 63, v4
	v_readlane_b32 s2, v251, 26
	v_ashrrev_i32_e32 v5, 31, v4
	v_readlane_b32 s3, v251, 27
	v_lshl_add_u64 v[4:5], s[20:21], 0, v[4:5]
	s_lshl_b32 s6, s85, 6
	v_mov_b64_e32 v[6:7], s[2:3]
	s_movk_i32 s2, 0x1400
	v_mad_u64_u32 v[8:9], s[4:5], v4, s2, v[6:7]
	v_mad_i32_i24 v9, v5, s2, v9
	s_lshl_b32 s4, s6, 1
	s_mov_b32 s5, s29
	v_lshl_add_u64 v[4:5], v[8:9], 0, s[4:5]
	v_mov_b32_e32 v41, v0
	v_lshl_add_u64 v[10:11], v[4:5], 0, v[40:41]
	global_load_dwordx4 v[112:115], v[10:11], off
	global_load_dwordx4 v[116:119], v[10:11], off offset:512
	s_lshl_b32 s22, s28, 1
	s_mov_b32 s23, s29
	v_lshlrev_b64 v[2:3], 14, v[2:3]
	v_lshl_add_u64 v[4:5], v[8:9], 0, s[22:23]
	v_lshl_add_u64 v[8:9], v[4:5], 0, v[40:41]
	global_load_dwordx4 v[120:123], v[8:9], off offset:1024
	global_load_dwordx4 v[124:127], v[8:9], off offset:1152
	v_lshl_add_u64 v[6:7], v[28:29], 0, v[2:3]
	v_lshl_add_u64 v[2:3], v[34:35], 1, v[6:7]
	global_load_dwordx4 v[128:131], v[2:3], off
	v_lshl_add_u64 v[2:3], v[36:37], 1, v[6:7]
	global_load_dwordx4 v[132:135], v[2:3], off
	s_waitcnt vmcnt(5)
	ds_write_b128 v47, v[112:115]
	s_waitcnt vmcnt(4)
	ds_write_b128 v47, v[116:119] offset:9216
	s_waitcnt vmcnt(3)
	ds_write_b16 v97, v120 offset:18432
	ds_write_b16_d16_hi v97, v120 offset:18576
	ds_write_b16 v97, v121 offset:18720
	ds_write_b16_d16_hi v97, v121 offset:18864
	ds_write_b16 v97, v122 offset:19008
	ds_write_b16_d16_hi v97, v122 offset:19152
	ds_write_b16 v97, v123 offset:19296
	ds_write_b16_d16_hi v97, v123 offset:19440
	s_waitcnt vmcnt(2)
	ds_write_b16 v98, v124 offset:18432
	ds_write_b16_d16_hi v97, v124 offset:27792
	ds_write_b16 v97, v125 offset:27936
	ds_write_b16_d16_hi v97, v125 offset:28080
	ds_write_b16 v97, v126 offset:28224
	ds_write_b16_d16_hi v97, v126 offset:28368
	ds_write_b16 v97, v127 offset:28512
	ds_write_b16_d16_hi v97, v127 offset:28656
	s_waitcnt vmcnt(1)
	ds_write_b128 v22, v[128:131] offset:36864
	s_waitcnt vmcnt(0)
	ds_write_b128 v99, v[132:135] offset:36864
	s_waitcnt lgkmcnt(0)
	s_barrier
	ds_read_b32 v2, v49
	ds_read_b128 v[4:7], v50
	ds_read_b128 v[8:11], v50 offset:16
	ds_read_b128 v[12:15], v47
	s_waitcnt lgkmcnt(0)
	v_lshlrev_b32_e32 v102, 16, v12
	v_and_b32_e32 v103, 0xffff0000, v12
	v_fma_f32 v3, v4, v102, 0
	v_lshlrev_b32_e32 v16, 16, v13
	v_fmac_f32_e32 v3, v5, v103
	v_and_b32_e32 v17, 0xffff0000, v13
	v_fmac_f32_e32 v3, v6, v16
	v_pk_mul_f32 v[4:5], v[2:3], v[16:17] op_sel_hi:[0,1]
	v_pk_mul_f32 v[12:13], v[2:3], v[102:103] op_sel_hi:[0,1]
	v_fmac_f32_e32 v3, v7, v17
	v_lshlrev_b32_e32 v6, 16, v14
	v_and_b32_e32 v7, 0xffff0000, v14
	v_fmac_f32_e32 v3, v8, v6
	v_lshlrev_b32_e32 v16, 16, v15
	v_fmac_f32_e32 v3, v9, v7
	v_and_b32_e32 v17, 0xffff0000, v15
	v_fmac_f32_e32 v3, v10, v16
	v_pk_mul_f32 v[8:9], v[2:3], v[16:17] op_sel_hi:[0,1]
	v_pk_mul_f32 v[14:15], v[2:3], v[6:7] op_sel_hi:[0,1]
	v_cvt_pk_bf16_f32 v7, v8, v9
	v_cvt_pk_bf16_f32 v6, v14, v15
	v_cvt_pk_bf16_f32 v5, v4, v5
	v_cvt_pk_bf16_f32 v4, v12, v13
	v_fmac_f32_e32 v3, v11, v17
	ds_write_b128 v47, v[4:7] offset:64512
	ds_bpermute_b32 v4, v51, v3
	s_waitcnt lgkmcnt(0)
	v_add_f32_e32 v3, v3, v4
	ds_bpermute_b32 v4, v52, v3
	s_waitcnt lgkmcnt(0)
	v_add_f32_e32 v3, v3, v4
	ds_bpermute_b32 v4, v53, v3
	s_and_saveexec_b64 s[24:25], s[42:43]
	s_cbranch_execz .LBB0_562
	s_waitcnt lgkmcnt(0)
	v_add_f32_e32 v3, v3, v4
	v_mul_f32_e32 v2, v2, v3
	ds_write_b32 v60, v2

; __device__ __forceinline__ int obid() { int b = __builtin_amdgcn_workgroup_id_x(); asm volatile("" : "+s"(b)); return b; }
; __device__ __forceinline__ f32x4 mma16(bf16x8 a, bf16x8 b, f32x4 c) { return __builtin_amdgcn_mfma_f32_16x16x32_bf16(a, b, c, 0, 0, 0); }
; __device__ __forceinline__ void gates_gemm(const bf16_t* XB, const bf16_t* WgT, const float* SS, const float* bias, float* GATES) {
;     ...
;     for (int rt = obid() * 8 + wid; rt < T_ / 16; rt += gridDim.x * 8) {
;         const size_t row = (size_t)rt * 16 + fr; f32x4 acc = {0.f, 0.f, 0.f, 0.f};
;         const bf16_t* xr = XB + row * 1024 + 8 * fq; const bf16_t* wr = WgT + fr * 1024 + 8 * fq;
; #pragma unroll 8
;         for (int kk = 0; kk < 32; ++kk) { const bf16x8 xa = *(const bf16x8*)(xr + kk * 32), wb = *(const bf16x8*)(wr + kk * 32); acc = mma16(wb, xa, acc); }
;         const float rs = rs_from_ss(SS, row); const f32x4 bv = *(const f32x4*)(bias + 4 * fq);
;         *(f32x4*)(GATES + row * 16 + 4 * fq) = acc * rs + bv;
;     }
.LBB0_641:
	v_lshl_add_u64 v[28:29], v[18:19], 0, s[24:25]
	v_lshl_add_u64 v[30:31], v[14:15], 0, s[24:25]
	global_load_dwordx4 v[36:39], v[28:29], off offset:-256
	global_load_dwordx4 v[40:43], v[30:31], off offset:-256
	global_load_dwordx4 v[44:47], v[28:29], off offset:-192
	global_load_dwordx4 v[48:51], v[30:31], off offset:-192
	global_load_dwordx4 v[52:55], v[28:29], off offset:-128
	global_load_dwordx4 v[56:59], v[30:31], off offset:-128
	global_load_dwordx4 v[60:63], v[28:29], off offset:-64
	global_load_dwordx4 v[64:67], v[30:31], off offset:-64
	global_load_dwordx4 v[68:71], v[28:29], off
	global_load_dwordx4 v[72:75], v[30:31], off
	global_load_dwordx4 v[76:79], v[28:29], off offset:64
	global_load_dwordx4 v[80:83], v[30:31], off offset:64
	global_load_dwordx4 v[84:87], v[28:29], off offset:128
	global_load_dwordx4 v[88:91], v[30:31], off offset:128
	global_load_dwordx4 v[92:95], v[28:29], off offset:192
	global_load_dwordx4 v[96:99], v[30:31], off offset:192
	s_add_u32 s24, s24, 0x200
	s_addc_u32 s25, s25, 0
	s_cmpk_eq_i32 s24, 0x800
	s_waitcnt vmcnt(14)
	v_mfma_f32_16x16x32_bf16 v[2:5], v[40:43], v[36:39], v[2:5]
	s_waitcnt vmcnt(12)
	v_mfma_f32_16x16x32_bf16 v[2:5], v[48:51], v[44:47], v[2:5]
	s_waitcnt vmcnt(10)
	v_mfma_f32_16x16x32_bf16 v[2:5], v[56:59], v[52:55], v[2:5]
	s_waitcnt vmcnt(8)
	v_mfma_f32_16x16x32_bf16 v[2:5], v[64:67], v[60:63], v[2:5]
	s_waitcnt vmcnt(6)
	v_mfma_f32_16x16x32_bf16 v[2:5], v[72:75], v[68:71], v[2:5]
	s_waitcnt vmcnt(4)
	v_mfma_f32_16x16x32_bf16 v[2:5], v[80:83], v[76:79], v[2:5]
	s_waitcnt vmcnt(2)
	v_mfma_f32_16x16x32_bf16 v[2:5], v[88:91], v[84:87], v[2:5]
	s_waitcnt vmcnt(0)
	v_mfma_f32_16x16x32_bf16 v[2:5], v[96:99], v[92:95], v[2:5]
	s_cbranch_scc0 .LBB0_641
	v_lshlrev_b64 v[34:35], 10, v[6:7]
	v_readlane_b32 s2, v251, 6
	v_lshl_or_b32 v34, v8, 6, v34
	v_readlane_b32 s3, v251, 7
	v_add_u32_e32 v6, s97, v6
	s_nop 0
	v_lshl_add_u64 v[30:31], s[2:3], 0, v[34:35]
	global_load_dwordx4 v[18:21], v[30:31], off offset:48
	global_load_dwordx4 v[22:25], v[30:31], off offset:32
	global_load_dwordx4 v[26:29], v[30:31], off
	s_nop 0
	global_load_dwordx4 v[30:33], v[30:31], off offset:16
	s_waitcnt vmcnt(0)
	v_pk_add_f32 v[28:29], v[28:29], v[32:33]
	v_pk_add_f32 v[26:27], v[26:27], v[30:31]
	v_pk_add_f32 v[24:25], v[28:29], v[24:25]
	v_pk_add_f32 v[22:23], v[26:27], v[22:23]
	v_pk_add_f32 v[20:21], v[24:25], v[20:21]
	v_pk_add_f32 v[18:19], v[22:23], v[18:19]
	s_nop 0
	v_pk_mov_b32 v[22:23], v[18:19], v[20:21] op_sel:[1,0]
	v_mov_b32_e32 v19, v21
	v_pk_add_f32 v[18:19], v[22:23], v[18:19]
	s_nop 0
	v_add_f32_e32 v1, v18, v19
	global_load_dwordx4 v[18:21], v[10:11], off
	v_fmamk_f32 v1, v1, 0x3a800000, v197
	v_cmp_gt_f32_e32 vcc, s1, v1
	v_mul_f32_e32 v7, 0x4b800000, v1
	s_nop 0
	v_cndmask_b32_e32 v1, v1, v7, vcc
	v_rsq_f32_e32 v1, v1
	s_nop 0
	v_mul_f32_e32 v7, 0x45800000, v1
	v_cndmask_b32_e32 v22, v1, v7, vcc
	v_cmp_lt_i32_e32 vcc, s15, v6
	s_or_b64 s[22:23], vcc, s[22:23]
	s_waitcnt vmcnt(0)
	v_pk_fma_f32 v[4:5], v[4:5], v[22:23], v[20:21] op_sel_hi:[1,0,1]
	v_pk_fma_f32 v[2:3], v[2:3], v[22:23], v[18:19] op_sel_hi:[1,0,1]
	v_lshl_add_u64 v[18:19], v[12:13], 0, v[34:35]
	global_store_dwordx4 v[18:19], v[2:5], off
	s_andn2_b64 exec, exec, s[22:23]
	s_cbranch_execnz .LBB0_640
